# MoBA S step hand-scheduled: logit bound folded into the MFMA accumulator init, 4 independent chains per tile
# speedup vs baseline: 1.0077x; 1.0022x over previous
;     ...
;       if (wid >= 4) {
;         const int sw = wid & 3, prow = (fr >> 2) * 8 + (fr & 3);
;         bf16x8 kf[4][2], kn[4][2];
; #pragma unroll
;         for (int a = 0; a < 4; ++a) { kf[a][0] = (bf16x8){0, 0, 0, 0, 0, 0, 0, 0}; kf[a][1] = kf[a][0]; }
;         int stepc = 0;
;         auto ssteps = [&](const int j, auto ownc) {
;           constexpr bool own = decltype(ownc)::value;
;           const int n = j < 0 ? 0 : (own ? 256 : cnt[j]), ntile = (n + 15) >> 4;
;     ...
;         for (int j = -1; j < blk; ++j) {
;           {
;             const bf16_t* kp = Mk + (krow0 + (j + 1) * 256 + 64 * sw + prow) * 64 + fq * 8;
; #pragma unroll
;             for (int g = 0; g < 2; ++g)
; #pragma unroll
;               for (int par = 0; par < 2; ++par) { kn[g * 2 + par][0] = *(const bf16x8*)(kp + (32 * g + 4 * par) * 64); kn[g * 2 + par][1] = *(const bf16x8*)(kp + (32 * g + 4 * par) * 64 + 32); }
.LBB0_651:
	s_and_b64 vcc, exec, s[16:17]
	s_cbranch_vccz .LBB0_542
	s_cmp_lt_i32 s18, 0
	s_mov_b32 s15, 0
	s_cbranch_scc1 .LBB0_664
	s_waitcnt vmcnt(15)
	v_mov_b32_e32 v34, 0
	s_waitcnt vmcnt(8)
	v_mov_b32_e32 v67, s51
	v_or_b32_e32 v66, s50, v192
	s_lshl_b64 s[98:99], s[50:51], 7
	s_add_u32 s98, s98, s26
	s_addc_u32 s99, s99, s27
	s_add_u32 s98, s98, 0x12300000
	s_addc_u32 s99, s99, 0
	v_and_b32_e32 v112, 63, v184
	v_lshlrev_b32_e32 v112, 4, v112
	v_bfe_u32 v113, v184, 6, 2
	v_lshl_or_b32 v112, v113, 13, v112
	v_mov_b32_e32 v113, 0
	v_lshl_add_u64 v[112:113], s[98:99], 0, v[112:113]

; DI float fast_exp2(float x) { return __builtin_amdgcn_exp2f(x); }
;     ...
; #pragma unroll
;         for (int a = 0; a < 4; ++a) { kf[a][0] = (bf16x8){0, 0, 0, 0, 0, 0, 0, 0}; kf[a][1] = kf[a][0]; }
;     ...
;                       float pe = fast_exp2(sv[par][i] - c2);
	v_sub_f32_e32 v108, 0, v217
	v_sub_f32_e32 v109, 0, v217
	v_sub_f32_e32 v110, 0, v217
	v_sub_f32_e32 v111, 0, v217
	s_mov_b32 s19, -1
	s_mov_b32 s14, s76
	v_mov_b32_e32 v35, v34
	s_waitcnt vmcnt(7)
	v_mov_b32_e32 v36, v34
	v_mov_b32_e32 v37, v34
	v_mov_b32_e32 v38, v34
	v_mov_b32_e32 v39, v34
	v_mov_b32_e32 v40, v34
	v_mov_b32_e32 v41, v34
	v_mov_b32_e32 v42, v34
	v_mov_b32_e32 v43, v34
	v_mov_b32_e32 v44, v34
	v_mov_b32_e32 v45, v34
	v_mov_b32_e32 v46, v34
	v_mov_b32_e32 v47, v34
	v_mov_b32_e32 v48, v34
	v_mov_b32_e32 v49, v34
	v_mov_b32_e32 v50, v34
	v_mov_b32_e32 v51, v34
	v_mov_b32_e32 v52, v34
	v_mov_b32_e32 v53, v34
	v_mov_b32_e32 v54, v34
	v_mov_b32_e32 v55, v34
	v_mov_b32_e32 v56, v34
	v_mov_b32_e32 v57, v34
	v_mov_b32_e32 v58, v34
	v_mov_b32_e32 v59, v34
	v_mov_b32_e32 v60, v34
	v_mov_b32_e32 v61, v34
	v_mov_b32_e32 v62, v34
	v_mov_b32_e32 v63, v34
	v_mov_b32_e32 v64, v34
	v_mov_b32_e32 v65, v34

; #define LAS __attribute__((address_space(3)))
; DI unsigned pk2(float lo, float hi) { f32x2 v = {lo, hi}; bf16v2 b = __builtin_convertvector(v, bf16v2); return __builtin_bit_cast(unsigned, b); }
; DI float fast_exp2(float x) { return __builtin_amdgcn_exp2f(x); }
; #define MFMA16(a, b, c) __builtin_amdgcn_mfma_f32_16x16x32_bf16((a), (b), (c), 0, 0, 0)
;     ...
;           for (int s0 = 0; s0 < ntile; s0 += 2, ++stepc) {
;             LAS unsigned char* pbuf = Pb + (stepc & 1) * 16384;
;             if (!(mode & 4))
; #pragma unroll
;             for (int tt = 0; tt < 2; ++tt) {
;               const int tile = s0 + tt;
;               if (tile < ntile) {
;                 const int rem = n - tile * 16;
;                 const int qidx = own ? tile * 16 + fr : (int)list[j * 256 + tile * 16 + (fr < rem ? fr : 0)];
;                 const bf16x8 q0 = *(const LAS bf16x8*)(Qs + qidx * MO_QS + fq * 16), q1 = *(const LAS bf16x8*)(Qs + qidx * MO_QS + 64 + fq * 16);
; #pragma unroll
;                 for (int g = 0; g < 2; ++g) {
;                   f32x4 sv[2];
; #pragma unroll
;                   for (int par = 0; par < 2; ++par) { sv[par] = MFMA16(kf[g * 2 + par][0], q0, ((f32x4){0.f, 0.f, 0.f, 0.f})); sv[par] = MFMA16(kf[g * 2 + par][1], q1, sv[par]); }
;                   float pv[2][4];
; #pragma unroll
;                   for (int par = 0; par < 2; ++par)
; #pragma unroll
;                     for (int i = 0; i < 4; ++i) {
;                       float pe = fast_exp2(sv[par][i] - c2);
;                       if (own) { const int key = 64 * sw + 32 * g + fq * 8 + 4 * par + i; if (key > qidx) pe = 0.f; }
;                       pv[par][i] = pe;
;                     }
;                   u32x4 pw; pw.x = pk2(pv[0][0], pv[0][1]); pw.y = pk2(pv[0][2], pv[0][3]); pw.z = pk2(pv[1][0], pv[1][1]); pw.w = pk2(pv[1][2], pv[1][3]);
;                   *(LAS u32x4*)(pbuf + tt * 8192 + (2 * sw + g) * 1024 + lane * 16) = pw;
;                 }
;               }
;             }
.LBB0_659:
	v_cmp_gt_i32_e32 vcc, s17, v193
	s_and_b32 s31, s15, 0x4000
	s_add_i32 s98, s17, -16
	s_cmp_ge_i32 s21, s19
	v_cndmask_b32_e32 v1, 0, v193, vcc
	v_add3_u32 v1, s30, v1, -16
	ds_read_u8 v1, v1
	s_cbranch_scc1 .Lms_one
	v_cmp_gt_i32_e32 vcc, s98, v193
	s_nop 1
	v_cndmask_b32_e32 v91, 0, v193, vcc
	v_add_u32_e32 v91, s30, v91
	ds_read_u8 v91, v91
	s_waitcnt lgkmcnt(1)
	v_mad_u32_u24 v1, v1, s59, v225
	ds_read_b128 v[92:95], v1
	ds_read_b128 v[96:99], v1 offset:64
	s_waitcnt lgkmcnt(2)
	v_mad_u32_u24 v91, v91, s59, v225
	ds_read_b128 v[100:103], v91
	ds_read_b128 v[104:107], v91 offset:64
	s_waitcnt lgkmcnt(3)
	v_mfma_f32_16x16x32_bf16 v[124:127], v[34:37], v[92:95], v[108:111]
	v_mfma_f32_16x16x32_bf16 v[128:131], v[42:45], v[92:95], v[108:111]
	v_mfma_f32_16x16x32_bf16 v[132:135], v[50:53], v[92:95], v[108:111]
	v_mfma_f32_16x16x32_bf16 v[136:139], v[58:61], v[92:95], v[108:111]
	s_waitcnt lgkmcnt(2)
	v_mfma_f32_16x16x32_bf16 v[124:127], v[38:41], v[96:99], v[124:127]
	v_mfma_f32_16x16x32_bf16 v[128:131], v[46:49], v[96:99], v[128:131]
	v_mfma_f32_16x16x32_bf16 v[132:135], v[54:57], v[96:99], v[132:135]
	v_mfma_f32_16x16x32_bf16 v[136:139], v[62:65], v[96:99], v[136:139]
	v_add_u32_e32 v1, s31, v226
	s_nop 7
	v_exp_f32_e32 v124, v124
	v_exp_f32_e32 v125, v125
	v_exp_f32_e32 v126, v126
	v_exp_f32_e32 v127, v127
	v_exp_f32_e32 v128, v128
	v_exp_f32_e32 v129, v129
	v_exp_f32_e32 v130, v130
	v_exp_f32_e32 v131, v131
	v_cvt_pk_bf16_f32 v140, v124, v125
	v_cvt_pk_bf16_f32 v141, v126, v127
	v_cvt_pk_bf16_f32 v142, v128, v129
	v_cvt_pk_bf16_f32 v143, v130, v131
	ds_write_b128 v1, v[140:143]
	v_exp_f32_e32 v132, v132
	v_exp_f32_e32 v133, v133
	v_exp_f32_e32 v134, v134
	v_exp_f32_e32 v135, v135
	v_exp_f32_e32 v136, v136
	v_exp_f32_e32 v137, v137
	v_exp_f32_e32 v138, v138
	v_exp_f32_e32 v139, v139
	v_cvt_pk_bf16_f32 v144, v132, v133
	v_cvt_pk_bf16_f32 v145, v134, v135
	v_cvt_pk_bf16_f32 v146, v136, v137
	v_cvt_pk_bf16_f32 v147, v138, v139
	ds_write_b128 v1, v[144:147] offset:1024
	s_waitcnt lgkmcnt(3)
	v_mfma_f32_16x16x32_bf16 v[148:151], v[34:37], v[100:103], v[108:111]
	v_mfma_f32_16x16x32_bf16 v[152:155], v[42:45], v[100:103], v[108:111]
	v_mfma_f32_16x16x32_bf16 v[156:159], v[50:53], v[100:103], v[108:111]
	v_mfma_f32_16x16x32_bf16 v[160:163], v[58:61], v[100:103], v[108:111]
	s_waitcnt lgkmcnt(2)
	v_mfma_f32_16x16x32_bf16 v[148:151], v[38:41], v[104:107], v[148:151]
	v_mfma_f32_16x16x32_bf16 v[152:155], v[46:49], v[104:107], v[152:155]
	v_mfma_f32_16x16x32_bf16 v[156:159], v[54:57], v[104:107], v[156:159]
	v_mfma_f32_16x16x32_bf16 v[160:163], v[62:65], v[104:107], v[160:163]
	v_add_u32_e32 v1, s31, v226
	s_nop 7
	v_exp_f32_e32 v148, v148
	v_exp_f32_e32 v149, v149
	v_exp_f32_e32 v150, v150
	v_exp_f32_e32 v151, v151
	v_exp_f32_e32 v152, v152
	v_exp_f32_e32 v153, v153
	v_exp_f32_e32 v154, v154
	v_exp_f32_e32 v155, v155
	v_cvt_pk_bf16_f32 v164, v148, v149
	v_cvt_pk_bf16_f32 v165, v150, v151
	v_cvt_pk_bf16_f32 v166, v152, v153
	v_cvt_pk_bf16_f32 v167, v154, v155
	ds_write_b128 v1, v[164:167] offset:8192
	v_exp_f32_e32 v156, v156
	v_exp_f32_e32 v157, v157
	v_exp_f32_e32 v158, v158
	v_exp_f32_e32 v159, v159
	v_exp_f32_e32 v160, v160
	v_exp_f32_e32 v161, v161
	v_exp_f32_e32 v162, v162
	v_exp_f32_e32 v163, v163
	v_cvt_pk_bf16_f32 v168, v156, v157
	v_cvt_pk_bf16_f32 v169, v158, v159
	v_cvt_pk_bf16_f32 v170, v160, v161
	v_cvt_pk_bf16_f32 v171, v162, v163
	ds_write_b128 v1, v[168:171] offset:9216
	s_branch .LBB0_658
.Lms_one:
	s_waitcnt lgkmcnt(0)
	v_mad_u32_u24 v1, v1, s59, v225
	ds_read_b128 v[68:71], v1
	ds_read_b128 v[72:75], v1 offset:64
	s_waitcnt lgkmcnt(1)
	v_mfma_f32_16x16x32_bf16 v[124:127], v[34:37], v[68:71], v[108:111]
	v_mfma_f32_16x16x32_bf16 v[128:131], v[42:45], v[68:71], v[108:111]
	v_mfma_f32_16x16x32_bf16 v[132:135], v[50:53], v[68:71], v[108:111]
	v_mfma_f32_16x16x32_bf16 v[136:139], v[58:61], v[68:71], v[108:111]
	s_waitcnt lgkmcnt(0)
	v_mfma_f32_16x16x32_bf16 v[124:127], v[38:41], v[72:75], v[124:127]
	v_mfma_f32_16x16x32_bf16 v[128:131], v[46:49], v[72:75], v[128:131]
	v_mfma_f32_16x16x32_bf16 v[132:135], v[54:57], v[72:75], v[132:135]
	v_mfma_f32_16x16x32_bf16 v[136:139], v[62:65], v[72:75], v[136:139]
	v_add_u32_e32 v1, s31, v226
	s_nop 7
	v_exp_f32_e32 v124, v124
	v_exp_f32_e32 v125, v125
	v_exp_f32_e32 v126, v126
	v_exp_f32_e32 v127, v127
	v_exp_f32_e32 v128, v128
	v_exp_f32_e32 v129, v129
	v_exp_f32_e32 v130, v130
	v_exp_f32_e32 v131, v131
	v_cvt_pk_bf16_f32 v140, v124, v125
	v_cvt_pk_bf16_f32 v141, v126, v127
	v_cvt_pk_bf16_f32 v142, v128, v129
	v_cvt_pk_bf16_f32 v143, v130, v131
	ds_write_b128 v1, v[140:143]
	v_exp_f32_e32 v132, v132
	v_exp_f32_e32 v133, v133
	v_exp_f32_e32 v134, v134
	v_exp_f32_e32 v135, v135
	v_exp_f32_e32 v136, v136
	v_exp_f32_e32 v137, v137
	v_exp_f32_e32 v138, v138
	v_exp_f32_e32 v139, v139
	v_cvt_pk_bf16_f32 v144, v132, v133
	v_cvt_pk_bf16_f32 v145, v134, v135
	v_cvt_pk_bf16_f32 v146, v136, v137
	v_cvt_pk_bf16_f32 v147, v138, v139
	ds_write_b128 v1, v[144:147] offset:1024
	s_branch .LBB0_658
